# v29 + MLA (KIND2) attention loop: 15 dead per-iteration zero-fill VALU stores removed (every path overwrites them before a read)
# baseline (speedup 1.0000x reference)
.LBB0_674:
	s_bitcmp1_b32 s31, 0
	s_cselect_b32 s31, 0xa000, 0
	v_add_u32_e32 v0, s31, v193
	v_add_u32_e32 v182, v0, v195
	v_add_u32_e32 v201, v0, v196
	v_add_u32_e32 v202, v0, v197
	v_add_u32_e32 v204, v0, v198
	ds_read_b128 v[214:217], v182 offset:0
	ds_read_b128 v[228:231], v201 offset:0
	ds_read_b128 v[232:235], v202 offset:0
	ds_read_b128 v[236:239], v204 offset:0
	ds_read_b128 v[240:243], v182 offset:128
	ds_read_b128 v[244:247], v201 offset:128
	s_waitcnt lgkmcnt(5)
	v_mfma_f32_32x32x16_bf16 v[80:95], v[214:217], v[96:99], 0
	ds_read_b128 v[214:217], v202 offset:128
	s_waitcnt lgkmcnt(5)
	v_mfma_f32_32x32x16_bf16 v[80:95], v[228:231], v[100:103], v[80:95]
	ds_read_b128 v[228:231], v204 offset:128
	s_waitcnt lgkmcnt(5)
	v_mfma_f32_32x32x16_bf16 v[80:95], v[232:235], v[104:107], v[80:95]
	ds_read_b128 v[232:235], v182 offset:256
	s_waitcnt lgkmcnt(5)
	v_mfma_f32_32x32x16_bf16 v[80:95], v[236:239], v[108:111], v[80:95]
	ds_read_b128 v[236:239], v201 offset:256
	s_waitcnt lgkmcnt(5)
	v_mfma_f32_32x32x16_bf16 v[80:95], v[240:243], v[112:115], v[80:95]
	ds_read_b128 v[240:243], v202 offset:256
	s_waitcnt lgkmcnt(5)
	v_mfma_f32_32x32x16_bf16 v[80:95], v[244:247], v[116:119], v[80:95]
	ds_read_b128 v[244:247], v204 offset:256
	s_waitcnt lgkmcnt(5)
	v_mfma_f32_32x32x16_bf16 v[80:95], v[214:217], v[120:123], v[80:95]
	s_waitcnt lgkmcnt(4)
	v_mfma_f32_32x32x16_bf16 v[80:95], v[228:231], v[124:127], v[80:95]
	s_waitcnt lgkmcnt(3)
	v_mfma_f32_32x32x16_bf16 v[80:95], v[232:235], v[128:131], v[80:95]
	s_waitcnt lgkmcnt(2)
	v_mfma_f32_32x32x16_bf16 v[80:95], v[236:239], v[132:135], v[80:95]
	s_waitcnt lgkmcnt(1)
	v_mfma_f32_32x32x16_bf16 v[80:95], v[240:243], v[136:139], v[80:95]
	s_waitcnt lgkmcnt(0)
	v_mfma_f32_32x32x16_bf16 v[80:95], v[244:247], v[140:143], v[80:95]
	s_nop 15
	s_nop 3

	s_mov_b32 s4, 0xf149f2ca
	v_max3_f32 v182, v80, v81, s4
	v_max3_f32 v201, v82, v83, v84
	v_max3_f32 v202, v85, v86, v87
	v_max3_f32 v182, v182, v88, v89
	v_max3_f32 v201, v201, v90, v91
	v_max3_f32 v202, v202, v92, v93
	v_max3_f32 v182, v182, v94, v95
	v_max3_f32 v182, v182, v201, v202
	v_mov_b32_e32 v201, v182
	s_nop 1
	v_permlane32_swap_b32_e32 v182, v201
	v_max3_f32 v205, v203, v182, v201
	v_mul_f32_e32 v182, 0xbdd53b94, v205
	v_fmamk_f32 v80, v80, 0x3dd53b94, v182
	v_exp_f32_e32 v80, v80
	v_fmamk_f32 v81, v81, 0x3dd53b94, v182
	v_exp_f32_e32 v81, v81
	v_fmamk_f32 v82, v82, 0x3dd53b94, v182
	v_exp_f32_e32 v82, v82
	v_fmamk_f32 v83, v83, 0x3dd53b94, v182
	v_sub_f32_e32 v201, v203, v205
	v_exp_f32_e32 v83, v83
	v_fmamk_f32 v84, v84, 0x3dd53b94, v182
	v_mul_f32_e32 v202, 0x3dd53b94, v201
	v_add_f32_e32 v201, 0, v80
	v_exp_f32_e32 v84, v84
	v_fmamk_f32 v85, v85, 0x3dd53b94, v182
	v_add_f32_e32 v201, v81, v201
	v_exp_f32_e32 v85, v85
	v_fmamk_f32 v86, v86, 0x3dd53b94, v182
	v_add_f32_e32 v201, v82, v201
	v_exp_f32_e32 v86, v86
	v_fmamk_f32 v87, v87, 0x3dd53b94, v182
	v_add_f32_e32 v201, v83, v201
	v_exp_f32_e32 v203, v87
	v_add_f32_e32 v87, v84, v201
	v_add_f32_e32 v87, v85, v87
	v_add_f32_e32 v87, v86, v87
	v_add_f32_e32 v201, v203, v87
	v_fmamk_f32 v87, v88, 0x3dd53b94, v182
	v_exp_f32_e32 v87, v87
	v_fmamk_f32 v88, v89, 0x3dd53b94, v182
	v_exp_f32_e32 v88, v88
	v_fmamk_f32 v89, v90, 0x3dd53b94, v182
	v_exp_f32_e32 v89, v89
	v_fmamk_f32 v90, v91, 0x3dd53b94, v182
	v_exp_f32_e32 v90, v90
	v_add_f32_e32 v91, v87, v201
	v_add_f32_e32 v91, v88, v91
	v_add_f32_e32 v91, v89, v91
	v_add_f32_e32 v201, v90, v91
	v_fmamk_f32 v91, v92, 0x3dd53b94, v182
	v_exp_f32_e32 v91, v91
	v_fmamk_f32 v92, v93, 0x3dd53b94, v182
	v_exp_f32_e32 v92, v92
	v_fmamk_f32 v93, v94, 0x3dd53b94, v182
	v_exp_f32_e32 v93, v93
	v_fmac_f32_e32 v182, 0x3dd53b94, v95
	v_exp_f32_e32 v94, v182
	v_add_f32_e32 v95, v91, v201
	v_add_f32_e32 v95, v92, v95
	v_exp_f32_e32 v182, v202
	v_add_f32_e32 v95, v93, v95
	v_add_f32_e32 v201, v94, v95
	v_mov_b32_e32 v202, v201
	s_nop 1
	v_permlane32_swap_b32_e32 v201, v202
	v_cmp_neq_f32_e32 vcc, 1.0, v182
	s_cbranch_vccz .LBB0_676
	v_pk_mul_f32 v[78:79], v[78:79], v[182:183] op_sel_hi:[1,0]
	v_pk_mul_f32 v[76:77], v[76:77], v[182:183] op_sel_hi:[1,0]
	v_pk_mul_f32 v[74:75], v[74:75], v[182:183] op_sel_hi:[1,0]
	v_pk_mul_f32 v[72:73], v[72:73], v[182:183] op_sel_hi:[1,0]
	v_pk_mul_f32 v[70:71], v[70:71], v[182:183] op_sel_hi:[1,0]
	v_pk_mul_f32 v[68:69], v[68:69], v[182:183] op_sel_hi:[1,0]
	v_pk_mul_f32 v[66:67], v[66:67], v[182:183] op_sel_hi:[1,0]
	v_pk_mul_f32 v[64:65], v[64:65], v[182:183] op_sel_hi:[1,0]
	v_pk_mul_f32 v[62:63], v[62:63], v[182:183] op_sel_hi:[1,0]
	v_pk_mul_f32 v[60:61], v[60:61], v[182:183] op_sel_hi:[1,0]
	v_pk_mul_f32 v[58:59], v[58:59], v[182:183] op_sel_hi:[1,0]
	v_pk_mul_f32 v[56:57], v[56:57], v[182:183] op_sel_hi:[1,0]
	v_pk_mul_f32 v[54:55], v[54:55], v[182:183] op_sel_hi:[1,0]
	v_pk_mul_f32 v[52:53], v[52:53], v[182:183] op_sel_hi:[1,0]
	v_pk_mul_f32 v[50:51], v[50:51], v[182:183] op_sel_hi:[1,0]
	v_pk_mul_f32 v[48:49], v[48:49], v[182:183] op_sel_hi:[1,0]
	v_pk_mul_f32 v[46:47], v[46:47], v[182:183] op_sel_hi:[1,0]
	v_pk_mul_f32 v[44:45], v[44:45], v[182:183] op_sel_hi:[1,0]
	v_pk_mul_f32 v[42:43], v[42:43], v[182:183] op_sel_hi:[1,0]
	v_pk_mul_f32 v[40:41], v[40:41], v[182:183] op_sel_hi:[1,0]
	v_pk_mul_f32 v[38:39], v[38:39], v[182:183] op_sel_hi:[1,0]
	v_pk_mul_f32 v[36:37], v[36:37], v[182:183] op_sel_hi:[1,0]
	v_pk_mul_f32 v[34:35], v[34:35], v[182:183] op_sel_hi:[1,0]
	v_pk_mul_f32 v[32:33], v[32:33], v[182:183] op_sel_hi:[1,0]
	v_pk_mul_f32 v[30:31], v[30:31], v[182:183] op_sel_hi:[1,0]
	v_pk_mul_f32 v[28:29], v[28:29], v[182:183] op_sel_hi:[1,0]
	v_pk_mul_f32 v[26:27], v[26:27], v[182:183] op_sel_hi:[1,0]
	v_pk_mul_f32 v[24:25], v[24:25], v[182:183] op_sel_hi:[1,0]
	v_pk_mul_f32 v[22:23], v[22:23], v[182:183] op_sel_hi:[1,0]
	v_pk_mul_f32 v[20:21], v[20:21], v[182:183] op_sel_hi:[1,0]
	v_pk_mul_f32 v[18:19], v[18:19], v[182:183] op_sel_hi:[1,0]
	v_pk_mul_f32 v[16:17], v[16:17], v[182:183] op_sel_hi:[1,0]
